# v25 + GEMM accumulators cleared between units by 11 MFMAs on an all-zero operand tuple (C=0) instead of 64 VALU moves
# baseline (speedup 1.0000x reference)
; template <class Epi, bool ALIGN_EPI>
; __device__ __forceinline__ void gemm_phase(LAS unsigned char* lds, const Gemm g, const StaticOrder& S, const Epi& E) {
;     ...
;         const bool has_next = S.next(ui + 1, nxt);
;         const char* nA = has_next ? (const char*)g.A + (size_t)nxt.pm * tstepA : cA; const char* nB = has_next ? (const char*)g.Bt + (size_t)nxt.pn * tstepB : cB;
;     ...
; #pragma unroll
;         for (int a = 0; a < 2; ++a)
; #pragma unroll
;             for (int b = 0; b < 2; ++b)
; #pragma unroll
;                 for (int m = 0; m < 4; ++m)
; #pragma unroll
;                     for (int n = 0; n < 2; ++n) acc[a][b][m][n] = (f32x4){0.f, 0.f, 0.f, 0.f};
;         cur = nxt; cA = nA; cB = nB; ++ui;
.LBB0_1261:
	s_ashr_i32 s57, s56, 31
	s_lshl_b64 s[16:17], s[56:57], 19
	s_add_u32 s16, s8, s16
	s_addc_u32 s17, s9, s17
	s_and_b64 s[18:19], s[40:41], exec
	s_cselect_b32 s24, s17, s21
	s_cselect_b32 s25, s16, s20
	s_ashr_i32 s61, s60, 31
	s_lshl_b64 s[18:19], s[60:61], 19
	s_add_u32 s18, s80, s18
	v_readlane_b32 s28, v251, 51
	s_addc_u32 s19, s28, s19
	s_and_b64 s[28:29], s[40:41], exec
	s_cselect_b32 s28, s19, s23
	s_cselect_b32 s29, s18, s22
	s_add_u32 s46, s22, 0x100
	s_addc_u32 s47, s23, 0
	s_add_u32 s20, s20, 0x40080
	s_addc_u32 s21, s21, 0
	s_mov_b32 s54, -2
	s_waitcnt vmcnt(0)
	v_mfma_f32_32x32x16_bf16 v[6:21], v[246:249], v[246:249], 0
	v_mfma_f32_32x32x16_bf16 v[22:37], v[246:249], v[246:249], 0
	v_mfma_f32_32x32x16_bf16 v[38:53], v[246:249], v[246:249], 0
	v_mfma_f32_32x32x16_bf16 v[54:69], v[246:249], v[246:249], 0
	v_mfma_f32_32x32x16_bf16 v[70:85], v[246:249], v[246:249], 0
	v_mfma_f32_32x32x16_bf16 v[86:101], v[246:249], v[246:249], 0
	v_mfma_f32_32x32x16_bf16 v[102:117], v[246:249], v[246:249], 0
	v_mfma_f32_16x16x32_bf16 v[118:121], v[246:249], v[246:249], 0
	v_mfma_f32_16x16x32_bf16 v[122:125], v[246:249], v[246:249], 0
	v_mfma_f32_16x16x32_bf16 v[126:129], v[246:249], v[246:249], 0
	v_mfma_f32_16x16x32_bf16 v[0:3], v[246:249], v[246:249], 0

; template <class Epi, bool ALIGN_EPI>
; __device__ __forceinline__ void gemm_phase(LAS unsigned char* lds, const Gemm g, const StaticOrder& S, const Epi& E) {
;     ...
; #pragma unroll
;         for (int a = 0; a < 2; ++a)
; #pragma unroll
;             for (int b = 0; b < 2; ++b)
; #pragma unroll
;                 for (int m = 0; m < 4; ++m)
; #pragma unroll
;                     for (int n = 0; n < 2; ++n) acc[a][b][m][n] = (f32x4){0.f, 0.f, 0.f, 0.f};
.LBB0_1291:
	s_add_u32 s28, s96, 0x100
	s_addc_u32 s29, s97, 0
	s_add_u32 s44, s50, 0x80
	s_addc_u32 s45, s51, 0
	s_mov_b32 s50, 0
	s_waitcnt vmcnt(0)
	v_mfma_f32_32x32x16_bf16 v[6:21], v[246:249], v[246:249], 0
	v_mfma_f32_32x32x16_bf16 v[22:37], v[246:249], v[246:249], 0
	v_mfma_f32_32x32x16_bf16 v[38:53], v[246:249], v[246:249], 0
	v_mfma_f32_32x32x16_bf16 v[54:69], v[246:249], v[246:249], 0
	v_mfma_f32_32x32x16_bf16 v[70:85], v[246:249], v[246:249], 0
	v_mfma_f32_32x32x16_bf16 v[86:101], v[246:249], v[246:249], 0
	v_mfma_f32_32x32x16_bf16 v[102:117], v[246:249], v[246:249], 0
	v_mfma_f32_16x16x32_bf16 v[118:121], v[246:249], v[246:249], 0
	v_mfma_f32_16x16x32_bf16 v[122:125], v[246:249], v[246:249], 0
	v_mfma_f32_16x16x32_bf16 v[126:129], v[246:249], v[246:249], 0
	v_mfma_f32_16x16x32_bf16 v[0:3], v[246:249], v[246:249], 0

; template <class Epi, bool ALIGN_EPI>
; __device__ __forceinline__ void gemm_phase(LAS unsigned char* lds, const Gemm g, const StaticOrder& S, const Epi& E) {
;     ...
; #pragma unroll
;         for (int a = 0; a < 2; ++a)
; #pragma unroll
;             for (int b = 0; b < 2; ++b)
; #pragma unroll
;                 for (int m = 0; m < 4; ++m)
; #pragma unroll
;                     for (int n = 0; n < 2; ++n) acc[a][b][m][n] = (f32x4){0.f, 0.f, 0.f, 0.f};
;         cur = nxt; cA = nA; cB = nB; ++ui;
.LBB0_1363:
	s_ashr_i32 s45, s44, 31
	s_lshl_b64 s[48:49], s[44:45], 18
	s_add_u32 s48, s7, s48
	s_addc_u32 s49, s4, s49
	s_and_b64 s[56:57], s[40:41], exec
	s_cselect_b32 s43, s49, s97
	s_cselect_b32 s45, s48, s96
	s_ashr_i32 s23, s22, 31
	s_lshl_b64 s[56:57], s[22:23], 18
	s_add_u32 s56, s46, s56
	s_addc_u32 s57, s47, s57
	s_and_b64 s[68:69], s[40:41], exec
	s_cselect_b32 s23, s57, s51
	s_cselect_b32 s61, s56, s50
	s_add_u32 s64, s50, 0x100
	s_addc_u32 s70, s51, 0
	s_add_u32 s96, s96, 0x20080
	s_addc_u32 s97, s97, 0
	s_mov_b32 s71, -2
	s_waitcnt vmcnt(0)
	v_mfma_f32_32x32x16_bf16 v[6:21], v[246:249], v[246:249], 0
	v_mfma_f32_32x32x16_bf16 v[22:37], v[246:249], v[246:249], 0
	v_mfma_f32_32x32x16_bf16 v[38:53], v[246:249], v[246:249], 0
	v_mfma_f32_32x32x16_bf16 v[54:69], v[246:249], v[246:249], 0
	v_mfma_f32_32x32x16_bf16 v[70:85], v[246:249], v[246:249], 0
	v_mfma_f32_32x32x16_bf16 v[86:101], v[246:249], v[246:249], 0
	v_mfma_f32_32x32x16_bf16 v[102:117], v[246:249], v[246:249], 0
	v_mfma_f32_16x16x32_bf16 v[118:121], v[246:249], v[246:249], 0
	v_mfma_f32_16x16x32_bf16 v[122:125], v[246:249], v[246:249], 0
	v_mfma_f32_16x16x32_bf16 v[126:129], v[246:249], v[246:249], 0
	v_mfma_f32_16x16x32_bf16 v[0:3], v[246:249], v[246:249], 0

; template <class Epi, bool ALIGN_EPI>
; __device__ __forceinline__ void gemm_phase(LAS unsigned char* lds, const Gemm g, const StaticOrder& S, const Epi& E) {
;     ...
; #pragma unroll
;         for (int a = 0; a < 2; ++a)
; #pragma unroll
;             for (int b = 0; b < 2; ++b)
; #pragma unroll
;                 for (int m = 0; m < 4; ++m)
; #pragma unroll
;                     for (int n = 0; n < 2; ++n) acc[a][b][m][n] = (f32x4){0.f, 0.f, 0.f, 0.f};
.LBB0_1426:
	s_add_u32 s56, s56, 0x100
	s_addc_u32 s57, s57, 0
	s_mov_b32 s50, 0
	v_mfma_f32_32x32x16_bf16 v[6:21], v[246:249], v[246:249], 0
	v_mfma_f32_32x32x16_bf16 v[22:37], v[246:249], v[246:249], 0
	v_mfma_f32_32x32x16_bf16 v[38:53], v[246:249], v[246:249], 0
	v_mfma_f32_32x32x16_bf16 v[54:69], v[246:249], v[246:249], 0
	v_mfma_f32_32x32x16_bf16 v[70:85], v[246:249], v[246:249], 0
	v_mfma_f32_32x32x16_bf16 v[86:101], v[246:249], v[246:249], 0
	v_mfma_f32_32x32x16_bf16 v[102:117], v[246:249], v[246:249], 0
	v_mfma_f32_16x16x32_bf16 v[118:121], v[246:249], v[246:249], 0
	v_mfma_f32_16x16x32_bf16 v[122:125], v[246:249], v[246:249], 0
	v_mfma_f32_16x16x32_bf16 v[126:129], v[246:249], v[246:249], 0
	v_mfma_f32_16x16x32_bf16 v[0:3], v[246:249], v[246:249], 0

; template <class Epi, bool ALIGN_EPI>
; __device__ __forceinline__ void gemm_phase(LAS unsigned char* lds, const Gemm g, const StaticOrder& S, const Epi& E) {
;     ...
;         const bool has_next = S.next(ui + 1, nxt);
;         const char* nA = has_next ? (const char*)g.A + (size_t)nxt.pm * tstepA : cA; const char* nB = has_next ? (const char*)g.Bt + (size_t)nxt.pn * tstepB : cB;
;     ...
; #pragma unroll
;         for (int a = 0; a < 2; ++a)
; #pragma unroll
;             for (int b = 0; b < 2; ++b)
; #pragma unroll
;                 for (int m = 0; m < 4; ++m)
; #pragma unroll
;                     for (int n = 0; n < 2; ++n) acc[a][b][m][n] = (f32x4){0.f, 0.f, 0.f, 0.f};
;         cur = nxt; cA = nA; cB = nB; ++ui;
.LBB0_1482:
	s_ashr_i32 s45, s44, 31
	s_lshl_b64 s[24:25], s[44:45], 19
	s_add_u32 s48, s8, s24
	s_addc_u32 s49, s9, s25
	s_and_b64 s[24:25], s[40:41], exec
	s_cselect_b32 s7, s49, s51
	s_cselect_b32 s21, s48, s50
	s_ashr_i32 s19, s18, 31
	s_lshl_b64 s[24:25], s[18:19], 19
	s_add_u32 s56, s5, s24
	s_addc_u32 s57, s53, s25
	s_and_b64 s[24:25], s[40:41], exec
	s_cselect_b32 s19, s57, s43
	s_cselect_b32 s23, s56, s42
	s_add_u32 s24, s42, 0x100
	s_addc_u32 s25, s43, 0
	s_add_u32 s42, s50, 0x40080
	s_addc_u32 s43, s51, 0
	s_mov_b32 s28, -2
	v_mfma_f32_32x32x16_bf16 v[6:21], v[246:249], v[246:249], 0
	v_mfma_f32_32x32x16_bf16 v[22:37], v[246:249], v[246:249], 0
	v_mfma_f32_32x32x16_bf16 v[38:53], v[246:249], v[246:249], 0
	v_mfma_f32_32x32x16_bf16 v[54:69], v[246:249], v[246:249], 0
	v_mfma_f32_32x32x16_bf16 v[70:85], v[246:249], v[246:249], 0
	v_mfma_f32_32x32x16_bf16 v[86:101], v[246:249], v[246:249], 0
	v_mfma_f32_32x32x16_bf16 v[102:117], v[246:249], v[246:249], 0
	v_mfma_f32_16x16x32_bf16 v[118:121], v[246:249], v[246:249], 0
	v_mfma_f32_16x16x32_bf16 v[122:125], v[246:249], v[246:249], 0
	v_mfma_f32_16x16x32_bf16 v[126:129], v[246:249], v[246:249], 0
	v_mfma_f32_16x16x32_bf16 v[0:3], v[246:249], v[246:249], 0
